# RWKV prep: a-LoRA weight fragments staged once per tile in LDS (LDS-DMA) and read with ds_read_b128 in the row-block loop; counted waits of the region re-derived
# speedup vs baseline: 1.0150x; 1.0003x over previous
; #define LAS __attribute__((address_space(3)))
; __device__ __forceinline__ f32x4 mfma16(bf16x8 a, bf16x8 b, f32x4 c) { return __builtin_amdgcn_mfma_f32_16x16x32_bf16(a, b, c, 0, 0, 0); }
; template <int K>
; __device__ __forceinline__ void row_gemm(f32x4 (&acc)[4], LAS const unsigned char* Arow, const bf16_t* Bt, int fr, int fq) {
;     ...
;         for (int n = 0; n < 4; ++n) bw[ks][n] = *(const bf16x8*)(Bt + (size_t)(16 * n + fr) * K + ks * 32 + fq * 8);
; #pragma unroll
;     for (int n = 0; n < 4; ++n) acc[n] = (f32x4){0.f, 0.f, 0.f, 0.f};
; #pragma unroll
;     for (int ks = 0; ks < K / 32; ++ks) { const bf16x8 a = *(LAS const bf16x8*)(Arow + (ks * 32 + fq * 8) * 2);
; #pragma unroll
;         for (int n = 0; n < 4; ++n) acc[n] = mfma16(bw[ks][n], a, acc[n]); }
; __device__ __forceinline__ void rwkv_prep_tile(LAS unsigned char* lds, const PrepArgs& P, int tt, int tid) {
;     ...
;         row_gemm<64>(aa, LAa + i * SW, P.a2t + (size_t)cb * 64, fr, fq);
;         row_gemm<64>(acc, LAw + i * SW, P.w2t + (size_t)cb * 64, fr, fq);
.LBB0_415:
	s_add_u32 s16, s28, 0x5b00000
	s_addc_u32 s17, s29, 0
	s_ashr_i32 s6, s21, 3
	s_ashr_i32 s22, s20, 6
	s_and_b32 s18, s20, 0xffffffc0
	s_and_b32 s6, s6, -8
	s_add_i32 s6, s6, s22
	s_lshl_b32 s7, s18, 2
	s_ashr_i32 s19, s18, 31
	s_add_i32 s34, s7, 0
	s_ashr_i32 s7, s6, 31
	s_lshl_b64 s[24:25], s[18:19], 6
	s_add_i32 s31, s34, 0x1bc00
	s_add_i32 s34, s34, 0x1c400
	s_lshl_b64 s[8:9], s[6:7], 12
	s_lshl_b64 s[52:53], s[18:19], 8
	s_ashr_i32 s23, s22, 31
	s_or_b32 s38, s18, 16
	s_or_b32 s39, s18, 32
	s_or_b32 s44, s18, 48
	s_lshl_b64 s[20:21], s[18:19], 1
	s_add_u32 s20, s28, s20
	s_addc_u32 s21, s29, s21
	s_add_u32 s20, s20, 0x7f00000
	s_addc_u32 s21, s21, 0
	s_lshl_b64 s[22:23], s[22:23], 2
	s_add_u32 s22, s28, s22
	s_addc_u32 s23, s29, s23
	s_add_u32 s22, s22, 0x8f00000
	s_addc_u32 s23, s23, 0
	s_lshl_b64 s[54:55], s[18:19], 7
	s_add_u32 s54, s28, s54
	v_lshlrev_b64 v[2:3], 1, v[2:3]
	s_addc_u32 s55, s29, s55
	v_lshlrev_b32_e32 v209, 2, v8
	v_lshlrev_b32_e32 v4, 7, v106
	v_cmp_eq_u32_e64 s[6:7], 0, v8
	v_lshl_add_u64 v[8:9], s[54:55], 0, v[2:3]
	s_mov_b64 s[54:55], 0x3a10000
	v_lshl_add_u64 v[10:11], v[8:9], 0, s[54:55]
	v_mov_b32_e32 v5, v1
	v_or_b32_e32 v12, 0x1000, v4
	v_mov_b32_e32 v13, v1
	v_or_b32_e32 v14, 0x1800, v4
	v_mov_b32_e32 v15, v1
	s_mov_b64 s[54:55], 0x3a10040
	s_add_u32 s52, s28, s52
	v_lshl_add_u64 v[108:109], v[10:11], 0, v[4:5]
	v_lshl_add_u64 v[110:111], v[10:11], 0, v[12:13]
	v_lshl_add_u64 v[112:113], v[10:11], 0, v[14:15]
	v_lshl_add_u64 v[10:11], v[8:9], 0, s[54:55]
	s_mov_b64 s[54:55], 0x3a00000
	s_addc_u32 s53, s29, s53
	v_lshl_add_u64 v[114:115], v[10:11], 0, v[12:13]
	v_lshl_add_u64 v[116:117], v[10:11], 0, v[14:15]
	v_lshl_add_u64 v[10:11], v[8:9], 0, s[54:55]
	s_mov_b64 s[54:55], 0x3a00040
	s_add_u32 s24, s28, s24
	v_lshl_add_u64 v[118:119], v[10:11], 0, v[4:5]
	v_lshl_add_u64 v[4:5], v[8:9], 0, s[54:55]
	s_addc_u32 s25, s29, s25
	v_lshlrev_b32_e32 v0, 6, v106
	v_lshl_add_u64 v[124:125], v[4:5], 0, v[12:13]
	v_lshl_add_u64 v[126:127], v[4:5], 0, v[14:15]
	v_lshl_add_u64 v[4:5], s[52:53], 0, v[2:3]
	v_lshl_add_u64 v[2:3], s[24:25], 0, v[2:3]
	v_lshl_add_u64 v[2:3], v[2:3], 0, v[0:1]
	s_mov_b64 s[24:25], 0x3a48000
	v_lshl_add_u64 v[154:155], v[2:3], 0, s[24:25]
	s_add_i32 s24, 0, 0x19000
	s_mov_b64 s[52:53], 0x3a20000
	v_mov_b32_e32 v0, s24
	s_movk_i32 s24, 0x50
	v_lshlrev_b32_e32 v6, 8, v106
	v_lshl_add_u64 v[8:9], v[4:5], 0, s[52:53]
	v_mov_b32_e32 v7, v1
	v_mad_u32_u24 v0, v106, s24, v0
	v_readlane_b32 s24, v255, 11
	v_lshl_add_u64 v[120:121], v[10:11], 0, v[12:13]
	v_lshl_add_u64 v[122:123], v[10:11], 0, v[14:15]
	v_lshl_add_u64 v[128:129], v[8:9], 0, v[6:7]
	v_or_b32_e32 v10, 0x1000, v6
	v_mov_b32_e32 v11, v1
	v_or_b32_e32 v12, 0x2000, v6
	v_or_b32_e32 v6, 0x3000, v6
	s_mov_b64 s[52:53], 0x3a20040
	v_mov_b32_e32 v2, s24
	s_movk_i32 s24, 0x110
	v_lshl_add_u64 v[130:131], v[8:9], 0, v[10:11]
	v_lshl_add_u64 v[132:133], v[8:9], 0, v[12:13]
	v_lshl_add_u64 v[134:135], v[8:9], 0, v[6:7]
	v_lshl_add_u64 v[8:9], v[4:5], 0, s[52:53]
	s_mov_b64 s[52:53], 0x3a20080
	v_mad_u32_u24 v210, v106, s24, v2
	s_and_b32 s24, s27, 7
	v_lshl_add_u64 v[136:137], v[8:9], 0, v[10:11]
	v_lshl_add_u64 v[138:139], v[8:9], 0, v[12:13]
	v_lshl_add_u64 v[140:141], v[8:9], 0, v[6:7]
	v_lshl_add_u64 v[8:9], v[4:5], 0, s[52:53]
	s_mov_b64 s[52:53], 0x3a200c0
	s_lshl_b32 s24, s24, 11
	s_lshl_b32 s25, s30, 6
	s_or_b32 s8, s8, s26
	v_mov_b32_e32 v107, v1
	v_lshl_add_u64 v[4:5], v[4:5], 0, s[52:53]
	s_add_i32 s24, s24, s25
	v_lshl_add_u64 v[2:3], s[8:9], 0, v[106:107]
	v_readlane_b32 s8, v254, 55
	v_lshl_add_u64 v[148:149], v[4:5], 0, v[10:11]
	v_lshl_add_u64 v[150:151], v[4:5], 0, v[12:13]
	v_lshl_add_u64 v[152:153], v[4:5], 0, v[6:7]
	v_or_b32_e32 v211, s24, v106
	s_movk_i32 s24, 0x90
	v_lshlrev_b64 v[4:5], 8, v[2:3]
	v_lshlrev_b64 v[2:3], 9, v[2:3]
	v_readlane_b32 s9, v254, 56
	s_mov_b32 s35, 0
	v_lshl_add_u64 v[142:143], v[8:9], 0, v[10:11]
	v_lshl_add_u64 v[144:145], v[8:9], 0, v[12:13]
	v_lshl_add_u64 v[146:147], v[8:9], 0, v[6:7]
	v_mad_u32_u24 v212, v106, s24, 0
	v_lshl_add_u64 v[156:157], s[92:93], 0, v[4:5]
	v_lshl_add_u64 v[158:159], s[8:9], 0, v[2:3]
	s_waitcnt lgkmcnt(0)
	s_barrier
	global_load_dwordx4 v[18:21], v[128:129], off
	global_load_dwordx4 v[22:25], v[128:129], off offset:64
	global_load_dwordx4 v[26:29], v[128:129], off offset:128
	global_load_dwordx4 v[30:33], v[128:129], off offset:192
	global_load_dwordx4 v[34:37], v[130:131], off
	global_load_dwordx4 v[38:41], v[136:137], off
	global_load_dwordx4 v[42:45], v[142:143], off
	global_load_dwordx4 v[46:49], v[148:149], off
	global_load_dwordx4 v[50:53], v[132:133], off
	global_load_dwordx4 v[54:57], v[138:139], off
	global_load_dwordx4 v[58:61], v[144:145], off
	global_load_dwordx4 v[62:65], v[150:151], off
	global_load_dwordx4 v[66:69], v[134:135], off
	global_load_dwordx4 v[70:73], v[140:141], off
	global_load_dwordx4 v[74:77], v[146:147], off
	global_load_dwordx4 v[78:81], v[152:153], off
	global_load_dwordx4 v[190:193], v[154:155], off
	global_load_dwordx4 v[216:219], v[154:155], off offset:1024
	global_load_dwordx4 v[220:223], v[154:155], off offset:2048
	global_load_dwordx4 v[224:227], v[154:155], off offset:3072
	v_lshrrev_b32_e32 v228, 6, v232
	s_nop 0
	v_readfirstlane_b32 s47, v228
	s_nop 3
	s_lshl_b32 s47, s47, 13
	s_add_i32 s47, s47, 0x8c00
	v_and_b32_e32 v215, 63, v232
	v_lshlrev_b32_e32 v215, 4, v215
	v_add_u32_e32 v215, s47, v215
	s_add_i32 m0, s47, 0
	s_nop 0
	global_load_lds_dwordx4 v[108:109], off
	s_mov_b64 s[48:49], 64
	v_lshl_add_u64 v[228:229], v[108:109], 0, s[48:49]
	s_add_i32 m0, s47, 1024
	s_nop 0
	global_load_lds_dwordx4 v[228:229], off
	s_mov_b64 s[48:49], 2048
	v_lshl_add_u64 v[228:229], v[108:109], 0, s[48:49]
	s_add_i32 m0, s47, 2048
	s_nop 0
	global_load_lds_dwordx4 v[228:229], off
	s_mov_b64 s[48:49], 2112
	v_lshl_add_u64 v[228:229], v[108:109], 0, s[48:49]
	s_add_i32 m0, s47, 3072
	s_nop 0
	global_load_lds_dwordx4 v[228:229], off
	s_add_i32 m0, s47, 4096
	s_nop 0
	global_load_lds_dwordx4 v[110:111], off
	s_add_i32 m0, s47, 5120
	s_nop 0
	global_load_lds_dwordx4 v[112:113], off
	s_add_i32 m0, s47, 6144
	s_nop 0
	global_load_lds_dwordx4 v[114:115], off
	s_add_i32 m0, s47, 7168
	s_nop 0
	global_load_lds_dwordx4 v[116:117], off
	s_mov_b32 s46, 0
	v_mov_b32_e32 v176, v210
	s_waitcnt vmcnt(0)

; #define LAS __attribute__((address_space(3)))
; __device__ __forceinline__ float sigmoidf_(float x) { return __builtin_amdgcn_rcpf(1.0f + __expf(-x)); }
; __device__ __forceinline__ f32x4 mfma16(bf16x8 a, bf16x8 b, f32x4 c) { return __builtin_amdgcn_mfma_f32_16x16x32_bf16(a, b, c, 0, 0, 0); }
; template <int K>
; __device__ __forceinline__ void row_gemm(f32x4 (&acc)[4], LAS const unsigned char* Arow, const bf16_t* Bt, int fr, int fq) {
;     bf16x8 bw[K / 32][4];
; #pragma unroll
;     for (int ks = 0; ks < K / 32; ++ks)
; #pragma unroll
;         for (int n = 0; n < 4; ++n) bw[ks][n] = *(const bf16x8*)(Bt + (size_t)(16 * n + fr) * K + ks * 32 + fq * 8);
; #pragma unroll
;     for (int n = 0; n < 4; ++n) acc[n] = (f32x4){0.f, 0.f, 0.f, 0.f};
; #pragma unroll
;     for (int ks = 0; ks < K / 32; ++ks) { const bf16x8 a = *(LAS const bf16x8*)(Arow + (ks * 32 + fq * 8) * 2);
; #pragma unroll
;         for (int n = 0; n < 4; ++n) acc[n] = mfma16(bw[ks][n], a, acc[n]); }
; }
; __device__ __forceinline__ void rwkv_prep_tile(LAS unsigned char* lds, const PrepArgs& P, int tt, int tid) {
;     ...
;         row_gemm<64>(aa, LAa + i * SW, P.a2t + (size_t)cb * 64, fr, fq);
;         row_gemm<64>(acc, LAw + i * SW, P.w2t + (size_t)cb * 64, fr, fq);
; #pragma unroll
;         for (int n = 0; n < 4; ++n) { const f32x4 a0v = *(LAS const f32x4*)(PRM + 1536 + cb + 16 * n + fq4), w0v = *(LAS const f32x4*)(PRM + 2048 + cb + 16 * n + fq4); f32x4 d;
; #pragma unroll
;             for (int j = 0; j < 4; ++j) { aa[n][j] = sigmoidf_(aa[n][j] + a0v[j]); d[j] = __expf(-0.6065306597f * sigmoidf_(acc[n][j] + w0v[j])); }
;             *(f32x4*)(P.Wd + ((size_t)p * SEQ + s0 + i) * 64 + 4 * fq4 + 4 * n) = d; }
.Lp4_skip_p:
	ds_read_b128 v[18:21], v215
	ds_read_b128 v[22:25], v215 offset:2048
	ds_read_b128 v[26:29], v215 offset:4096
	v_add_u32_e32 v62, v212, v208
	ds_read_b128 v[34:37], v62 offset:9216
	ds_read_b128 v[30:33], v62 offset:9280
	ds_read_b128 v[38:41], v215 offset:1024
	ds_read_b128 v[42:45], v215 offset:5120
	ds_read_b128 v[46:49], v215 offset:3072
	global_load_dwordx4 v[50:53], v[118:119], off
	global_load_dwordx4 v[58:61], v[118:119], off offset:64
	v_lshlrev_b32_e32 v162, 2, v98
	v_add_u32_e32 v71, s34, v162
	v_lshl_add_u64 v[88:89], v[156:157], 0, s[10:11]
	v_ashrrev_i32_e32 v163, 31, v162
	s_mov_b32 s24, 0xe100000
	v_ashrrev_i32_e32 v99, 31, v98
	s_waitcnt vmcnt(2) lgkmcnt(4)
	v_mfma_f32_16x16x32_bf16 v[18:21], v[18:21], v[34:37], 0
	s_waitcnt vmcnt(2) lgkmcnt(5)
	v_mfma_f32_16x16x32_bf16 v[54:57], v[26:29], v[34:37], 0
	global_load_dwordx4 v[26:29], v[118:119], off offset:2048
	v_mfma_f32_16x16x32_bf16 v[22:25], v[22:25], v[34:37], 0
	s_waitcnt vmcnt(3) lgkmcnt(1)
	v_mfma_f32_16x16x32_bf16 v[34:37], v[42:45], v[34:37], 0
	ds_read_b128 v[42:45], v62
	ds_read_b128 v[62:65], v62 offset:64
	global_load_dwordx4 v[66:69], v[120:121], off
	global_load_dwordx4 v[76:79], v[118:119], off offset:2112
	s_waitcnt vmcnt(4) lgkmcnt(1)
	v_mfma_f32_16x16x32_bf16 v[50:53], v[50:53], v[42:45], 0
	v_mfma_f32_16x16x32_bf16 v[22:25], v[46:49], v[30:33], v[22:25]
	s_waitcnt vmcnt(3) lgkmcnt(0)
	v_mfma_f32_16x16x32_bf16 v[50:53], v[58:61], v[62:65], v[50:53]
	v_lshl_add_u64 v[58:59], v[162:163], 2, v[88:89]
	v_add_co_u32_e32 v58, vcc, s24, v58
	s_waitcnt vmcnt(1) lgkmcnt(2)
	v_mfma_f32_16x16x32_bf16 v[66:69], v[66:69], v[42:45], 0
	v_addc_co_u32_e32 v59, vcc, 0, v59, vcc
	s_and_b64 vcc, exec, s[4:5]
	v_mfma_f32_16x16x32_bf16 v[94:97], v[26:29], v[42:45], 0
	global_load_dwordx4 v[26:29], v[122:123], off
	s_waitcnt vmcnt(1) lgkmcnt(2)
	v_mfma_f32_16x16x32_bf16 v[76:79], v[76:79], v[62:65], v[94:97]
	s_waitcnt vmcnt(0) lgkmcnt(2)
	s_cmp_eq_u32 s35, 0
	s_cbranch_scc1 .Lp4_carry
	v_mov_b32_dpp v166, v128 row_ror:1 row_mask:0xf bank_mask:0x1
	v_mov_b32_dpp v167, v129 row_ror:1 row_mask:0xf bank_mask:0x1
	v_mov_b32_dpp v170, v130 row_ror:1 row_mask:0xf bank_mask:0x1
	v_mov_b32_dpp v171, v131 row_ror:1 row_mask:0xf bank_mask:0x1
	v_mov_b32_dpp v194, v132 row_ror:1 row_mask:0xf bank_mask:0x1
	v_mov_b32_dpp v195, v133 row_ror:1 row_mask:0xf bank_mask:0x1
	v_mov_b32_dpp v180, v134 row_ror:1 row_mask:0xf bank_mask:0x1
	v_mov_b32_dpp v181, v135 row_ror:1 row_mask:0xf bank_mask:0x1
	v_mov_b32_dpp v200, v136 row_ror:1 row_mask:0xf bank_mask:0x1
	v_mov_b32_dpp v201, v137 row_ror:1 row_mask:0xf bank_mask:0x1
	v_mov_b32_dpp v202, v138 row_ror:1 row_mask:0xf bank_mask:0x1
	v_mov_b32_dpp v203, v139 row_ror:1 row_mask:0xf bank_mask:0x1
	v_mov_b32_dpp v198, v140 row_ror:1 row_mask:0xf bank_mask:0x1
	v_mov_b32_dpp v199, v141 row_ror:1 row_mask:0xf bank_mask:0x1
	v_mov_b32_dpp v182, v142 row_ror:1 row_mask:0xf bank_mask:0x1
	v_mov_b32_dpp v183, v143 row_ror:1 row_mask:0xf bank_mask:0x1
	v_mov_b32_dpp v72, v144 row_ror:1 row_mask:0xf bank_mask:0x1
	v_mov_b32_dpp v73, v145 row_ror:1 row_mask:0xf bank_mask:0x1
	v_mov_b32_dpp v84, v146 row_ror:1 row_mask:0xf bank_mask:0x1
	v_mov_b32_dpp v85, v147 row_ror:1 row_mask:0xf bank_mask:0x1
	v_mov_b32_dpp v92, v148 row_ror:1 row_mask:0xf bank_mask:0x1
	v_mov_b32_dpp v93, v149 row_ror:1 row_mask:0xf bank_mask:0x1
	v_mov_b32_dpp v100, v150 row_ror:1 row_mask:0xf bank_mask:0x1
	v_mov_b32_dpp v101, v151 row_ror:1 row_mask:0xf bank_mask:0x1
	v_mov_b32_dpp v166, v164 row_shr:1 row_mask:0xf bank_mask:0xf
	v_mov_b32_dpp v167, v165 row_shr:1 row_mask:0xf bank_mask:0xf
	v_mov_b32_dpp v170, v168 row_shr:1 row_mask:0xf bank_mask:0xf
	v_mov_b32_dpp v171, v169 row_shr:1 row_mask:0xf bank_mask:0xf
	v_mov_b32_dpp v194, v176 row_shr:1 row_mask:0xf bank_mask:0xf
	v_mov_b32_dpp v195, v177 row_shr:1 row_mask:0xf bank_mask:0xf
	v_mov_b32_dpp v180, v172 row_shr:1 row_mask:0xf bank_mask:0xf
	v_mov_b32_dpp v181, v173 row_shr:1 row_mask:0xf bank_mask:0xf
	v_mov_b32_dpp v200, v196 row_shr:1 row_mask:0xf bank_mask:0xf
	v_mov_b32_dpp v201, v197 row_shr:1 row_mask:0xf bank_mask:0xf
	v_mov_b32_dpp v202, v184 row_shr:1 row_mask:0xf bank_mask:0xf
	v_mov_b32_dpp v203, v185 row_shr:1 row_mask:0xf bank_mask:0xf
	v_mov_b32_dpp v198, v178 row_shr:1 row_mask:0xf bank_mask:0xf
	v_mov_b32_dpp v199, v179 row_shr:1 row_mask:0xf bank_mask:0xf
	v_mov_b32_dpp v182, v174 row_shr:1 row_mask:0xf bank_mask:0xf
	v_mov_b32_dpp v183, v175 row_shr:1 row_mask:0xf bank_mask:0xf
	v_mov_b32_dpp v72, v74 row_shr:1 row_mask:0xf bank_mask:0xf
	v_mov_b32_dpp v73, v75 row_shr:1 row_mask:0xf bank_mask:0xf
	v_mov_b32_dpp v84, v86 row_shr:1 row_mask:0xf bank_mask:0xf
	v_mov_b32_dpp v85, v87 row_shr:1 row_mask:0xf bank_mask:0xf
	v_mov_b32_dpp v92, v104 row_shr:1 row_mask:0xf bank_mask:0xf
	v_mov_b32_dpp v93, v105 row_shr:1 row_mask:0xf bank_mask:0xf
	v_mov_b32_dpp v100, v102 row_shr:1 row_mask:0xf bank_mask:0xf
	v_mov_b32_dpp v101, v103 row_shr:1 row_mask:0xf bank_mask:0xf
; #define LAS __attribute__((address_space(3)))
; __device__ __forceinline__ void st_bf4(bf16_t* p, f32x4 v) { u32x2 w; w.x = cvt_pk_bf16(v[0], v[1]); w.y = cvt_pk_bf16(v[2], v[3]); *(u32x2*)p = w; }
; __device__ __forceinline__ float sigmoidf_(float x) { return __builtin_amdgcn_rcpf(1.0f + __expf(-x)); }
; __device__ __forceinline__ f32x4 mfma16(bf16x8 a, bf16x8 b, f32x4 c) { return __builtin_amdgcn_mfma_f32_16x16x32_bf16(a, b, c, 0, 0, 0); }
; template <int K>
; __device__ __forceinline__ void row_gemm(f32x4 (&acc)[4], LAS const unsigned char* Arow, const bf16_t* Bt, int fr, int fq) {
;     bf16x8 bw[K / 32][4];
; #pragma unroll
;     for (int ks = 0; ks < K / 32; ++ks)
; #pragma unroll
;         for (int n = 0; n < 4; ++n) bw[ks][n] = *(const bf16x8*)(Bt + (size_t)(16 * n + fr) * K + ks * 32 + fq * 8);
; #pragma unroll
;     for (int n = 0; n < 4; ++n) acc[n] = (f32x4){0.f, 0.f, 0.f, 0.f};
; #pragma unroll
;     for (int ks = 0; ks < K / 32; ++ks) { const bf16x8 a = *(LAS const bf16x8*)(Arow + (ks * 32 + fq * 8) * 2);
; #pragma unroll
;         for (int n = 0; n < 4; ++n) acc[n] = mfma16(bw[ks][n], a, acc[n]); }
; }
; __device__ __forceinline__ void rwkv_prep_tile(LAS unsigned char* lds, const PrepArgs& P, int tt, int tid) {
;     ...
;         row_gemm<64>(aa, LAa + i * SW, P.a2t + (size_t)cb * 64, fr, fq);
;         row_gemm<64>(acc, LAw + i * SW, P.w2t + (size_t)cb * 64, fr, fq);
; #pragma unroll
;         for (int n = 0; n < 4; ++n) { const f32x4 a0v = *(LAS const f32x4*)(PRM + 1536 + cb + 16 * n + fq4), w0v = *(LAS const f32x4*)(PRM + 2048 + cb + 16 * n + fq4); f32x4 d;
; #pragma unroll
;             for (int j = 0; j < 4; ++j) { aa[n][j] = sigmoidf_(aa[n][j] + a0v[j]); d[j] = __expf(-0.6065306597f * sigmoidf_(acc[n][j] + w0v[j])); }
;             *(f32x4*)(P.Wd + ((size_t)p * SEQ + s0 + i) * 64 + 4 * fq4 + 4 * n) = d; }
;         row_gemm<128>(acc, LAg + i * SG, P.g2t + (size_t)cb * 128, fr, fq);
; #pragma unroll
;         for (int n = 0; n < 4; ++n) st_bf4(P.Go + (size_t)(t0 + i) * 512 + cb + 16 * n + fq4, acc[n]);
;         if (P.layer > 0) row_gemm<32>(acc, LAvv + i * SVV, P.v2t + (size_t)cb * 32, fr, fq);
.Lp4_carry:
	v_mov_b32_e32 v128, v164
	v_mov_b32_e32 v129, v165
	v_mov_b32_e32 v130, v168
	v_mov_b32_e32 v131, v169
	v_mov_b32_e32 v132, v176
	v_mov_b32_e32 v133, v177
	v_mov_b32_e32 v134, v172
	v_mov_b32_e32 v135, v173
	v_mov_b32_e32 v136, v196
	v_mov_b32_e32 v137, v197
	v_mov_b32_e32 v138, v184
	v_mov_b32_e32 v139, v185
	v_mov_b32_e32 v140, v178
	v_mov_b32_e32 v141, v179
	v_mov_b32_e32 v142, v174
	v_mov_b32_e32 v143, v175
	v_mov_b32_e32 v144, v74
	v_mov_b32_e32 v145, v75
	v_mov_b32_e32 v146, v86
	v_mov_b32_e32 v147, v87
	v_mov_b32_e32 v148, v104
	v_mov_b32_e32 v149, v105
	v_mov_b32_e32 v150, v102
	v_mov_b32_e32 v151, v103
	v_mfma_f32_16x16x32_bf16 v[42:45], v[26:29], v[42:45], 0
	v_mfma_f32_16x16x32_bf16 v[26:29], v[38:41], v[30:33], v[18:21]
	s_nop 2
	ds_read_b128 v[18:21], v215 offset:6144
	global_load_dwordx4 v[46:49], v[124:125], off
	ds_read_b128 v[38:41], v215 offset:7168
	s_waitcnt vmcnt(0) lgkmcnt(1)
	v_mfma_f32_16x16x32_bf16 v[46:49], v[46:49], v[62:65], v[66:69]
	v_mfma_f32_16x16x32_bf16 v[18:21], v[18:21], v[30:33], v[54:57]
	s_nop 2
	global_load_dwordx4 v[54:57], v[126:127], off
	ds_read_b128 v[94:97], v71
	ds_read_b128 v[204:207], v71 offset:64
	s_waitcnt vmcnt(1) lgkmcnt(2)
	v_mfma_f32_16x16x32_bf16 v[30:33], v[38:41], v[30:33], v[34:37]
	s_waitcnt lgkmcnt(1)
	v_add_f32_e32 v50, v50, v94
	v_add_f32_e32 v51, v51, v95
	v_add_f32_e32 v52, v52, v96
	v_add_f32_e32 v53, v53, v97
	v_mul_f32_e32 v50, 0xbfb8aa3b, v50
	v_mul_f32_e32 v51, 0xbfb8aa3b, v51
	v_mul_f32_e32 v52, 0xbfb8aa3b, v52
	v_mul_f32_e32 v53, 0xbfb8aa3b, v53
	v_exp_f32_e32 v50, v50
	v_exp_f32_e32 v51, v51
	v_exp_f32_e32 v52, v52
	v_exp_f32_e32 v53, v53
	v_add_f32_e32 v50, 1.0, v50
	v_add_f32_e32 v51, 1.0, v51
	v_add_f32_e32 v52, 1.0, v52
	v_add_f32_e32 v53, 1.0, v53
	v_rcp_f32_e32 v50, v50
	v_rcp_f32_e32 v51, v51
	v_rcp_f32_e32 v52, v52
	v_rcp_f32_e32 v53, v53
	v_mul_f32_e32 v50, 0xbf1b4598, v50
	v_mul_f32_e32 v51, 0xbf1b4598, v51
	v_mul_f32_e32 v52, 0xbf1b4598, v52
	v_mul_f32_e32 v53, 0xbf1b4598, v53
	v_mul_f32_e32 v50, 0x3fb8aa3b, v50
	v_mul_f32_e32 v51, 0x3fb8aa3b, v51
	v_mul_f32_e32 v52, 0x3fb8aa3b, v52
	v_mul_f32_e32 v53, 0x3fb8aa3b, v53
	v_exp_f32_e32 v50, v50
	v_exp_f32_e32 v51, v51
	v_exp_f32_e32 v52, v52
	v_exp_f32_e32 v53, v53
	s_waitcnt vmcnt(0) lgkmcnt(2)
	v_mfma_f32_16x16x32_bf16 v[42:45], v[54:57], v[62:65], v[42:45]
	ds_read_b128 v[60:63], v71 offset:128
	ds_read_b128 v[64:67], v71 offset:192
	s_waitcnt lgkmcnt(2)
	v_add_f32_e32 v54, v76, v204
	v_add_f32_e32 v55, v77, v205
	v_add_f32_e32 v56, v78, v206
	v_add_f32_e32 v57, v79, v207
	v_mul_f32_e32 v54, 0xbfb8aa3b, v54
	v_mul_f32_e32 v55, 0xbfb8aa3b, v55
	v_mul_f32_e32 v56, 0xbfb8aa3b, v56
	v_mul_f32_e32 v57, 0xbfb8aa3b, v57
	s_waitcnt lgkmcnt(1)
	v_add_f32_e32 v46, v46, v60
	v_add_f32_e32 v47, v47, v61
	v_add_f32_e32 v48, v48, v62
	v_add_f32_e32 v49, v49, v63
	v_exp_f32_e32 v54, v54
	v_exp_f32_e32 v55, v55
	v_exp_f32_e32 v56, v56
	v_exp_f32_e32 v57, v57
	v_mul_f32_e32 v46, 0xbfb8aa3b, v46
	v_mul_f32_e32 v47, 0xbfb8aa3b, v47
	v_mul_f32_e32 v48, 0xbfb8aa3b, v48
	v_mul_f32_e32 v49, 0xbfb8aa3b, v49
	s_waitcnt lgkmcnt(0)
	v_add_f32_e32 v42, v42, v64
	v_add_f32_e32 v43, v43, v65
	v_add_f32_e32 v44, v44, v66
	v_add_f32_e32 v45, v45, v67
	v_exp_f32_e32 v46, v46
	v_exp_f32_e32 v47, v47
	v_exp_f32_e32 v48, v48
	v_exp_f32_e32 v49, v49
	v_mul_f32_e32 v42, 0xbfb8aa3b, v42
	v_mul_f32_e32 v43, 0xbfb8aa3b, v43
	v_mul_f32_e32 v44, 0xbfb8aa3b, v44
	v_mul_f32_e32 v45, 0xbfb8aa3b, v45
	v_exp_f32_e32 v42, v42
	v_exp_f32_e32 v43, v43
	v_exp_f32_e32 v44, v44
	v_exp_f32_e32 v45, v45
	v_add_f32_e32 v54, 1.0, v54
	v_add_f32_e32 v55, 1.0, v55
	v_add_f32_e32 v56, 1.0, v56
	v_add_f32_e32 v57, 1.0, v57
	v_rcp_f32_e32 v54, v54
	v_rcp_f32_e32 v55, v55
	v_rcp_f32_e32 v56, v56
	v_rcp_f32_e32 v57, v57
	v_add_f32_e32 v46, 1.0, v46
	v_add_f32_e32 v47, 1.0, v47
	v_add_f32_e32 v48, 1.0, v48
	v_add_f32_e32 v49, 1.0, v49
	v_rcp_f32_e32 v46, v46
	v_rcp_f32_e32 v47, v47
	v_rcp_f32_e32 v48, v48
	v_rcp_f32_e32 v49, v49
	v_add_f32_e32 v42, 1.0, v42
	v_add_f32_e32 v43, 1.0, v43
	v_add_f32_e32 v44, 1.0, v44
	v_add_f32_e32 v45, 1.0, v45
	v_rcp_f32_e32 v42, v42
	v_rcp_f32_e32 v43, v43
	v_rcp_f32_e32 v44, v44
	v_rcp_f32_e32 v45, v45
	v_mul_f32_e32 v54, 0xbf1b4598, v54
	v_mul_f32_e32 v55, 0xbf1b4598, v55
	v_mul_f32_e32 v56, 0xbf1b4598, v56
	v_mul_f32_e32 v57, 0xbf1b4598, v57
	v_mul_f32_e32 v54, 0x3fb8aa3b, v54
	v_mul_f32_e32 v55, 0x3fb8aa3b, v55
	v_mul_f32_e32 v56, 0x3fb8aa3b, v56
	v_mul_f32_e32 v57, 0x3fb8aa3b, v57
	v_mul_f32_e32 v46, 0xbf1b4598, v46
	v_mul_f32_e32 v47, 0xbf1b4598, v47
	v_mul_f32_e32 v48, 0xbf1b4598, v48
	v_mul_f32_e32 v49, 0xbf1b4598, v49
	v_exp_f32_e32 v54, v54
	v_exp_f32_e32 v55, v55
	v_exp_f32_e32 v56, v56
	v_exp_f32_e32 v57, v57
	v_mul_f32_e32 v46, 0x3fb8aa3b, v46
	v_mul_f32_e32 v47, 0x3fb8aa3b, v47
	v_mul_f32_e32 v48, 0x3fb8aa3b, v48
	v_mul_f32_e32 v49, 0x3fb8aa3b, v49
	v_mul_f32_e32 v42, 0xbf1b4598, v42
	v_mul_f32_e32 v43, 0xbf1b4598, v43
	v_mul_f32_e32 v44, 0xbf1b4598, v44
	v_mul_f32_e32 v45, 0xbf1b4598, v45
	v_exp_f32_e32 v46, v46
	v_exp_f32_e32 v47, v47
	v_exp_f32_e32 v48, v48
	v_exp_f32_e32 v49, v49
	v_mul_f32_e32 v42, 0x3fb8aa3b, v42
	v_mul_f32_e32 v43, 0x3fb8aa3b, v43
	v_mul_f32_e32 v44, 0x3fb8aa3b, v44
	v_mul_f32_e32 v45, 0x3fb8aa3b, v45
	v_exp_f32_e32 v42, v42
	v_exp_f32_e32 v43, v43
	v_exp_f32_e32 v44, v44
	v_exp_f32_e32 v45, v45
	global_store_dwordx4 v[58:59], v[50:53], off
	global_store_dwordx4 v[58:59], v[54:57], off offset:16
	global_store_dwordx4 v[58:59], v[46:49], off offset:32
	global_store_dwordx4 v[58:59], v[42:45], off offset:48
	s_nop 1
	v_add_u32_e32 v34, s31, v162
	ds_read_b128 v[46:49], v34
	ds_read_b128 v[42:45], v34 offset:64
	ds_read_b128 v[38:41], v34 offset:128
	ds_read_b128 v[34:37], v34 offset:192
	s_cbranch_vccnz .LBB0_427
	v_add_u32_e32 v58, v0, v208
	ds_read_b128 v[62:65], v58
	s_waitcnt lgkmcnt(0)
	v_mfma_f32_16x16x32_bf16 v[66:69], v[190:193], v[62:65], 0
	v_mfma_f32_16x16x32_bf16 v[58:61], v[216:219], v[62:65], 0
	v_mfma_f32_16x16x32_bf16 v[54:57], v[220:223], v[62:65], 0
	v_mfma_f32_16x16x32_bf16 v[62:65], v[224:227], v[62:65], 0
